# attention: priority 1 while a wave issues its 12 K-fragment reads, 0 otherwise (on the combination version)
# baseline (speedup 1.0000x reference)
; DI void attn_item(const Params& p, int item, char* smem) {
;     ...
; #pragma unroll
;     for (int d0 = 0; d0 < 6; ++d0) {
;       const bf16x8 a0 = *(const bf16x8*)(Kc + r32 * KSL + d0 * 16 + hi * 8);
;       const bf16x8 a1 = *(const bf16x8*)(Kc + (32 + r32) * KSL + d0 * 16 + hi * 8);
;       p0 = __builtin_amdgcn_mfma_f32_32x32x16_bf16(a0, qr[d0], p0, 0, 0, 0);
;       p1 = __builtin_amdgcn_mfma_f32_32x32x16_bf16(a1, qr[d0], p1, 0, 0, 0);
;     }
;     float mx = p0[0];
; #pragma unroll
;     for (int i = 1; i < 16; ++i) mx = fmaxf(mx, p0[i]);
; #pragma unroll
;     for (int i = 0; i < 16; ++i) mx = fmaxf(mx, p1[i]);
;     { auto rr = __builtin_amdgcn_permlane32_swap(__float_as_uint(mx), __float_as_uint(mx), false, false);
;       mx = fmaxf(__uint_as_float(rr[0]), __uint_as_float(rr[1])); }
;     if (!__all(mx - mrun <= 8.f)) {
;       const float mn = fmaxf(mrun, mx);
;       const float alpha = __builtin_amdgcn_exp2f(mrun - mn);
;       mrun = mn; lrun *= alpha;
; #pragma unroll
;       for (int i = 0; i < 16; ++i) { o0[i] *= alpha; o1[i] *= alpha; }
;     }
;     float ps = 0.f;
; #pragma unroll
;     for (int i = 0; i < 16; ++i) { p0[i] = __builtin_amdgcn_exp2f(p0[i] - mrun); ps += p0[i]; }
; #pragma unroll
;     for (int i = 0; i < 16; ++i) { p1[i] = __builtin_amdgcn_exp2f(p1[i] - mrun); ps += p1[i]; }
;     lrun += ps;
.LBB0_531:
	s_setprio 1
	ds_read_b128 v[164:167], v154
	ds_read_b128 v[168:171], v154 offset:32
	ds_read_b128 v[172:175], v154 offset:64
	ds_read_b128 v[176:179], v154 offset:96
	ds_read_b128 v[180:183], v154 offset:128
	ds_read_b128 v[184:187], v154 offset:160
	ds_read_b128 v[188:191], v154 offset:6656
	ds_read_b128 v[158:161], v154 offset:6688
	ds_read_b128 v[192:195], v154 offset:6720
	ds_read_b128 v[212:215], v154 offset:6752
	ds_read_b128 v[216:219], v154 offset:6784
	ds_read_b128 v[10:13], v154 offset:6816
	s_setprio 0
	s_waitcnt lgkmcnt(11)
	v_mfma_f32_32x32x16_bf16 v[64:79], v[164:167], v[80:83], v[196:211]
	s_waitcnt lgkmcnt(10)
	v_mfma_f32_32x32x16_bf16 v[64:79], v[168:171], v[84:87], v[64:79]
	s_waitcnt lgkmcnt(9)
	v_mfma_f32_32x32x16_bf16 v[64:79], v[172:175], v[88:91], v[64:79]
	s_waitcnt lgkmcnt(8)
	v_mfma_f32_32x32x16_bf16 v[64:79], v[176:179], v[92:95], v[64:79]
	s_waitcnt lgkmcnt(7)
	v_mfma_f32_32x32x16_bf16 v[64:79], v[180:183], v[96:99], v[64:79]
	s_waitcnt lgkmcnt(6)
	v_mfma_f32_32x32x16_bf16 v[64:79], v[184:187], v[100:103], v[64:79]
	s_waitcnt lgkmcnt(5)
	v_mfma_f32_32x32x16_bf16 v[48:63], v[188:191], v[80:83], v[196:211]
	s_waitcnt lgkmcnt(4)
	v_mfma_f32_32x32x16_bf16 v[48:63], v[158:161], v[84:87], v[48:63]
	s_nop 7
	v_exp_f32_e32 v168, v64
	v_exp_f32_e32 v169, v65
	v_exp_f32_e32 v170, v66
	v_exp_f32_e32 v171, v67
	v_exp_f32_e32 v172, v68
	v_exp_f32_e32 v173, v69
	v_exp_f32_e32 v174, v70
	v_exp_f32_e32 v175, v71
	s_waitcnt lgkmcnt(3)
	v_mfma_f32_32x32x16_bf16 v[48:63], v[192:195], v[88:91], v[48:63]
	s_waitcnt lgkmcnt(2)
	v_mfma_f32_32x32x16_bf16 v[48:63], v[212:215], v[92:95], v[48:63]
	v_exp_f32_e32 v176, v72
	v_exp_f32_e32 v177, v73
	v_exp_f32_e32 v178, v74
	v_exp_f32_e32 v179, v75
	v_exp_f32_e32 v180, v76
	v_exp_f32_e32 v181, v77
	v_exp_f32_e32 v182, v78
	v_exp_f32_e32 v183, v79
	s_waitcnt lgkmcnt(1)
	v_mfma_f32_32x32x16_bf16 v[48:63], v[216:219], v[96:99], v[48:63]
	s_waitcnt lgkmcnt(0)
	v_mfma_f32_32x32x16_bf16 v[48:63], v[10:13], v[100:103], v[48:63]
	v_add_f32_e32 v0, v168, v169
	v_add_f32_e32 v0, v170, v0
	v_add_f32_e32 v0, v171, v0
	v_add_f32_e32 v0, v172, v0
	v_add_f32_e32 v0, v173, v0
	v_add_f32_e32 v0, v174, v0
	v_add_f32_e32 v0, v175, v0
	v_add_f32_e32 v0, v176, v0
	v_add_f32_e32 v0, v177, v0
	v_add_f32_e32 v0, v178, v0
	v_add_f32_e32 v0, v179, v0
	v_add_f32_e32 v0, v180, v0
	v_add_f32_e32 v0, v181, v0
	v_add_f32_e32 v0, v182, v0
	v_add_f32_e32 v0, v183, v0
	v_exp_f32_e32 v184, v48
	v_exp_f32_e32 v185, v49
	v_exp_f32_e32 v186, v50
	v_exp_f32_e32 v187, v51
	v_exp_f32_e32 v188, v52
	v_exp_f32_e32 v189, v53
	v_exp_f32_e32 v190, v54
	v_exp_f32_e32 v191, v55
	v_exp_f32_e32 v158, v56
	v_exp_f32_e32 v159, v57
	v_exp_f32_e32 v160, v58
	v_exp_f32_e32 v161, v59
	v_exp_f32_e32 v164, v60
	v_exp_f32_e32 v165, v61
	v_exp_f32_e32 v166, v62
	v_exp_f32_e32 v167, v63
	v_add_f32_e32 v0, v184, v0
	v_add_f32_e32 v0, v185, v0
	v_add_f32_e32 v0, v186, v0
	v_add_f32_e32 v0, v187, v0
	v_add_f32_e32 v0, v188, v0
	v_add_f32_e32 v0, v189, v0
	v_add_f32_e32 v0, v190, v0
	v_add_f32_e32 v0, v191, v0
	v_add_f32_e32 v0, v158, v0
	v_add_f32_e32 v0, v159, v0
	v_add_f32_e32 v0, v160, v0
	v_add_f32_e32 v0, v161, v0
	v_add_f32_e32 v0, v164, v0
	v_add_f32_e32 v0, v165, v0
	v_add_f32_e32 v0, v166, v0
	v_add_f32_e32 v0, v167, v0
	v_cmp_ge_f32_e32 vcc, s98, v0
	s_cmp_eq_u64 vcc, exec
	s_cbranch_scc1 .LBB0_533
; DI void attn_item(const Params& p, int item, char* smem) {
;     ...
;     { auto rr = __builtin_amdgcn_permlane32_swap(__float_as_uint(mx), __float_as_uint(mx), false, false);
;       mx = fmaxf(__uint_as_float(rr[0]), __uint_as_float(rr[1])); }
;     if (!__all(mx - mrun <= 8.f)) {
;       const float mn = fmaxf(mrun, mx);
;       const float alpha = __builtin_amdgcn_exp2f(mrun - mn);
;       mrun = mn; lrun *= alpha;
; #pragma unroll
;       for (int i = 0; i < 16; ++i) { o0[i] *= alpha; o1[i] *= alpha; }
;     }
;     float ps = 0.f;
; #pragma unroll
;     for (int i = 0; i < 16; ++i) { p0[i] = __builtin_amdgcn_exp2f(p0[i] - mrun); ps += p0[i]; }
; #pragma unroll
;     for (int i = 0; i < 16; ++i) { p1[i] = __builtin_amdgcn_exp2f(p1[i] - mrun); ps += p1[i]; }
	v_max_f32_e32 v10, v64, v65
	v_max3_f32 v10, v10, v66, v67
	v_max3_f32 v10, v10, v68, v69
	v_max3_f32 v10, v10, v70, v71
	v_max3_f32 v10, v10, v72, v73
	v_max3_f32 v10, v10, v74, v75
	v_max3_f32 v10, v10, v76, v77
	v_max3_f32 v10, v10, v78, v79
	v_max3_f32 v10, v10, v48, v49
	v_max3_f32 v10, v10, v50, v51
	v_max3_f32 v10, v10, v52, v53
	v_max3_f32 v10, v10, v54, v55
	v_max3_f32 v10, v10, v56, v57
	v_max3_f32 v10, v10, v58, v59
	v_max3_f32 v10, v10, v60, v61
	v_max3_f32 v10, v10, v62, v63
	v_mov_b32_e32 v11, v10
	s_nop 1
	v_permlane32_swap_b32_e32 v10, v11
	v_max_f32_e32 v10, v10, v11
	v_max_f32_e32 v11, s99, v10
	v_max_f32_e32 v10, 0, v11
	s_mov_b32 s98, 0x46000000
	v_exp_f32_e64 v10, -v10
	s_mov_b32 s99, 0
	v_sub_f32_e32 v196, v196, v11
	v_mul_f32_e32 v157, v157, v10
	v_pk_mul_f32 v[46:47], v[46:47], v[10:11] op_sel_hi:[1,0]
	v_pk_mul_f32 v[44:45], v[44:45], v[10:11] op_sel_hi:[1,0]
	v_pk_mul_f32 v[42:43], v[42:43], v[10:11] op_sel_hi:[1,0]
	v_pk_mul_f32 v[40:41], v[40:41], v[10:11] op_sel_hi:[1,0]
	v_pk_mul_f32 v[38:39], v[38:39], v[10:11] op_sel_hi:[1,0]
	v_pk_mul_f32 v[36:37], v[36:37], v[10:11] op_sel_hi:[1,0]
	v_pk_mul_f32 v[34:35], v[34:35], v[10:11] op_sel_hi:[1,0]
	v_pk_mul_f32 v[32:33], v[32:33], v[10:11] op_sel_hi:[1,0]
	v_pk_mul_f32 v[30:31], v[30:31], v[10:11] op_sel_hi:[1,0]
	v_pk_mul_f32 v[28:29], v[28:29], v[10:11] op_sel_hi:[1,0]
	v_pk_mul_f32 v[26:27], v[26:27], v[10:11] op_sel_hi:[1,0]
	v_pk_mul_f32 v[24:25], v[24:25], v[10:11] op_sel_hi:[1,0]
	v_pk_mul_f32 v[22:23], v[22:23], v[10:11] op_sel_hi:[1,0]
	v_pk_mul_f32 v[20:21], v[20:21], v[10:11] op_sel_hi:[1,0]
	v_pk_mul_f32 v[18:19], v[18:19], v[10:11] op_sel_hi:[1,0]
	v_pk_mul_f32 v[16:17], v[16:17], v[10:11] op_sel_hi:[1,0]
	v_mov_b32_e32 v197, v196
	v_mov_b32_e32 v198, v196
	v_mov_b32_e32 v199, v196
	v_mov_b32_e32 v200, v196
	v_mov_b32_e32 v201, v196
	v_mov_b32_e32 v202, v196
	v_mov_b32_e32 v203, v196
	v_mov_b32_e32 v204, v196
	v_mov_b32_e32 v205, v196
	v_mov_b32_e32 v206, v196
	v_mov_b32_e32 v207, v196
	v_mov_b32_e32 v208, v196
	v_mov_b32_e32 v209, v196
	v_mov_b32_e32 v210, v196
	v_mov_b32_e32 v211, v196
	v_sub_f32_e32 v64, v64, v11
	v_sub_f32_e32 v65, v65, v11
	v_sub_f32_e32 v66, v66, v11
	v_sub_f32_e32 v67, v67, v11
	v_sub_f32_e32 v68, v68, v11
	v_sub_f32_e32 v69, v69, v11
	v_sub_f32_e32 v70, v70, v11
	v_sub_f32_e32 v71, v71, v11
	v_sub_f32_e32 v72, v72, v11
	v_sub_f32_e32 v73, v73, v11
	v_sub_f32_e32 v74, v74, v11
	v_sub_f32_e32 v75, v75, v11
	v_sub_f32_e32 v76, v76, v11
	v_sub_f32_e32 v77, v77, v11
	v_sub_f32_e32 v78, v78, v11
	v_sub_f32_e32 v79, v79, v11
	v_sub_f32_e32 v48, v48, v11
	v_sub_f32_e32 v49, v49, v11
	v_sub_f32_e32 v50, v50, v11
	v_sub_f32_e32 v51, v51, v11
	v_sub_f32_e32 v52, v52, v11
	v_sub_f32_e32 v53, v53, v11
	v_sub_f32_e32 v54, v54, v11
	v_sub_f32_e32 v55, v55, v11
	v_sub_f32_e32 v56, v56, v11
	v_sub_f32_e32 v57, v57, v11
	v_sub_f32_e32 v58, v58, v11
	v_sub_f32_e32 v59, v59, v11
	v_sub_f32_e32 v60, v60, v11
	v_sub_f32_e32 v61, v61, v11
	v_sub_f32_e32 v62, v62, v11
	v_sub_f32_e32 v63, v63, v11
	v_exp_f32_e32 v168, v64
	v_exp_f32_e32 v169, v65
	v_exp_f32_e32 v170, v66
	v_exp_f32_e32 v171, v67
	v_exp_f32_e32 v172, v68
	v_exp_f32_e32 v173, v69
	v_exp_f32_e32 v174, v70
	v_exp_f32_e32 v175, v71
	v_exp_f32_e32 v176, v72
	v_exp_f32_e32 v177, v73
	v_exp_f32_e32 v178, v74
	v_exp_f32_e32 v179, v75
	v_exp_f32_e32 v180, v76
	v_exp_f32_e32 v181, v77
	v_exp_f32_e32 v182, v78
	v_exp_f32_e32 v183, v79
	v_exp_f32_e32 v184, v48
	v_exp_f32_e32 v185, v49
	v_exp_f32_e32 v186, v50
	v_exp_f32_e32 v187, v51
	v_exp_f32_e32 v188, v52
	v_exp_f32_e32 v189, v53
	v_exp_f32_e32 v190, v54
	v_exp_f32_e32 v191, v55
	v_exp_f32_e32 v158, v56
	v_exp_f32_e32 v159, v57
	v_exp_f32_e32 v160, v58
	v_exp_f32_e32 v161, v59
	v_exp_f32_e32 v164, v60
	v_exp_f32_e32 v165, v61
	v_exp_f32_e32 v166, v62
	v_exp_f32_e32 v167, v63
	v_add_f32_e32 v0, v168, v169
	v_add_f32_e32 v0, v170, v0
	v_add_f32_e32 v0, v171, v0
	v_add_f32_e32 v0, v172, v0
	v_add_f32_e32 v0, v173, v0
	v_add_f32_e32 v0, v174, v0
	v_add_f32_e32 v0, v175, v0
	v_add_f32_e32 v0, v176, v0
	v_add_f32_e32 v0, v177, v0
	v_add_f32_e32 v0, v178, v0
	v_add_f32_e32 v0, v179, v0
	v_add_f32_e32 v0, v180, v0
	v_add_f32_e32 v0, v181, v0
	v_add_f32_e32 v0, v182, v0
	v_add_f32_e32 v0, v183, v0
	v_add_f32_e32 v0, v184, v0
	v_add_f32_e32 v0, v185, v0
	v_add_f32_e32 v0, v186, v0
	v_add_f32_e32 v0, v187, v0
	v_add_f32_e32 v0, v188, v0
	v_add_f32_e32 v0, v189, v0
	v_add_f32_e32 v0, v190, v0
	v_add_f32_e32 v0, v191, v0
	v_add_f32_e32 v0, v158, v0
	v_add_f32_e32 v0, v159, v0
	v_add_f32_e32 v0, v160, v0
	v_add_f32_e32 v0, v161, v0
	v_add_f32_e32 v0, v164, v0
	v_add_f32_e32 v0, v165, v0
	v_add_f32_e32 v0, v166, v0
	v_add_f32_e32 v0, v167, v0

; DI void attn_item(const Params& p, int item, char* smem) {
;     ...
; #pragma unroll
;     for (int d0 = 0; d0 < 6; ++d0) {
;       const bf16x8 a0 = *(const bf16x8*)(Kc + r32 * KSL + d0 * 16 + hi * 8);
;       const bf16x8 a1 = *(const bf16x8*)(Kc + (32 + r32) * KSL + d0 * 16 + hi * 8);
;       p0 = __builtin_amdgcn_mfma_f32_32x32x16_bf16(a0, qr[d0], p0, 0, 0, 0);
;       p1 = __builtin_amdgcn_mfma_f32_32x32x16_bf16(a1, qr[d0], p1, 0, 0, 0);
;     }
;     float mx = p0[0];
; #pragma unroll
;     for (int i = 1; i < 16; ++i) mx = fmaxf(mx, p0[i]);
; #pragma unroll
;     for (int i = 0; i < 16; ++i) mx = fmaxf(mx, p1[i]);
;     { auto rr = __builtin_amdgcn_permlane32_swap(__float_as_uint(mx), __float_as_uint(mx), false, false);
;       mx = fmaxf(__uint_as_float(rr[0]), __uint_as_float(rr[1])); }
;     if (!__all(mx - mrun <= 8.f)) {
;       const float mn = fmaxf(mrun, mx);
;       const float alpha = __builtin_amdgcn_exp2f(mrun - mn);
;       mrun = mn; lrun *= alpha;
; #pragma unroll
;       for (int i = 0; i < 16; ++i) { o0[i] *= alpha; o1[i] *= alpha; }
;     }
;     float ps = 0.f;
; #pragma unroll
;     for (int i = 0; i < 16; ++i) { p0[i] = __builtin_amdgcn_exp2f(p0[i] - mrun); ps += p0[i]; }
; #pragma unroll
;     for (int i = 0; i < 16; ++i) { p1[i] = __builtin_amdgcn_exp2f(p1[i] - mrun); ps += p1[i]; }
;     lrun += ps;
.LBB0_535:
	s_setprio 1
	ds_read_b128 v[164:167], v154 offset:13312
	ds_read_b128 v[168:171], v154 offset:13344
	ds_read_b128 v[172:175], v154 offset:13376
	ds_read_b128 v[176:179], v154 offset:13408
	ds_read_b128 v[180:183], v154 offset:13440
	ds_read_b128 v[184:187], v154 offset:13472
	ds_read_b128 v[188:191], v154 offset:19968
	ds_read_b128 v[158:161], v154 offset:20000
	ds_read_b128 v[192:195], v154 offset:20032
	ds_read_b128 v[212:215], v154 offset:20064
	ds_read_b128 v[216:219], v154 offset:20096
	ds_read_b128 v[10:13], v154 offset:20128
	s_setprio 0
	s_waitcnt lgkmcnt(11)
	v_mfma_f32_32x32x16_bf16 v[64:79], v[164:167], v[80:83], v[196:211]
	s_waitcnt lgkmcnt(10)
	v_mfma_f32_32x32x16_bf16 v[64:79], v[168:171], v[84:87], v[64:79]
	s_waitcnt lgkmcnt(9)
	v_mfma_f32_32x32x16_bf16 v[64:79], v[172:175], v[88:91], v[64:79]
	s_waitcnt lgkmcnt(8)
	v_mfma_f32_32x32x16_bf16 v[64:79], v[176:179], v[92:95], v[64:79]
	s_waitcnt lgkmcnt(7)
	v_mfma_f32_32x32x16_bf16 v[64:79], v[180:183], v[96:99], v[64:79]
	s_waitcnt lgkmcnt(6)
	v_mfma_f32_32x32x16_bf16 v[64:79], v[184:187], v[100:103], v[64:79]
	s_waitcnt lgkmcnt(5)
	v_mfma_f32_32x32x16_bf16 v[48:63], v[188:191], v[80:83], v[196:211]
	s_waitcnt lgkmcnt(4)
	v_mfma_f32_32x32x16_bf16 v[48:63], v[158:161], v[84:87], v[48:63]
	s_nop 7
	v_exp_f32_e32 v168, v64
	v_exp_f32_e32 v169, v65
	v_exp_f32_e32 v170, v66
	v_exp_f32_e32 v171, v67
	v_exp_f32_e32 v172, v68
	v_exp_f32_e32 v173, v69
	v_exp_f32_e32 v174, v70
	v_exp_f32_e32 v175, v71
	s_waitcnt lgkmcnt(3)
	v_mfma_f32_32x32x16_bf16 v[48:63], v[192:195], v[88:91], v[48:63]
	s_waitcnt lgkmcnt(2)
	v_mfma_f32_32x32x16_bf16 v[48:63], v[212:215], v[92:95], v[48:63]
	v_exp_f32_e32 v176, v72
	v_exp_f32_e32 v177, v73
	v_exp_f32_e32 v178, v74
	v_exp_f32_e32 v179, v75
	v_exp_f32_e32 v180, v76
	v_exp_f32_e32 v181, v77
	v_exp_f32_e32 v182, v78
	v_exp_f32_e32 v183, v79
	s_waitcnt lgkmcnt(1)
	v_mfma_f32_32x32x16_bf16 v[48:63], v[216:219], v[96:99], v[48:63]
	s_waitcnt lgkmcnt(0)
	v_mfma_f32_32x32x16_bf16 v[48:63], v[10:13], v[100:103], v[48:63]
	v_add_f32_e32 v0, v168, v169
	v_add_f32_e32 v0, v170, v0
	v_add_f32_e32 v0, v171, v0
	v_add_f32_e32 v0, v172, v0
	v_add_f32_e32 v0, v173, v0
	v_add_f32_e32 v0, v174, v0
	v_add_f32_e32 v0, v175, v0
	v_add_f32_e32 v0, v176, v0
	v_add_f32_e32 v0, v177, v0
	v_add_f32_e32 v0, v178, v0
	v_add_f32_e32 v0, v179, v0
	v_add_f32_e32 v0, v180, v0
	v_add_f32_e32 v0, v181, v0
	v_add_f32_e32 v0, v182, v0
	v_add_f32_e32 v0, v183, v0
	v_exp_f32_e32 v184, v48
	v_exp_f32_e32 v185, v49
	v_exp_f32_e32 v186, v50
	v_exp_f32_e32 v187, v51
	v_exp_f32_e32 v188, v52
	v_exp_f32_e32 v189, v53
	v_exp_f32_e32 v190, v54
	v_exp_f32_e32 v191, v55
	v_exp_f32_e32 v158, v56
	v_exp_f32_e32 v159, v57
	v_exp_f32_e32 v160, v58
	v_exp_f32_e32 v161, v59
	v_exp_f32_e32 v164, v60
	v_exp_f32_e32 v165, v61
	v_exp_f32_e32 v166, v62
	v_exp_f32_e32 v167, v63
	v_add_f32_e32 v0, v184, v0
	v_add_f32_e32 v0, v185, v0
	v_add_f32_e32 v0, v186, v0
	v_add_f32_e32 v0, v187, v0
	v_add_f32_e32 v0, v188, v0
	v_add_f32_e32 v0, v189, v0
	v_add_f32_e32 v0, v190, v0
	v_add_f32_e32 v0, v191, v0
	v_add_f32_e32 v0, v158, v0
	v_add_f32_e32 v0, v159, v0
	v_add_f32_e32 v0, v160, v0
	v_add_f32_e32 v0, v161, v0
	v_add_f32_e32 v0, v164, v0
	v_add_f32_e32 v0, v165, v0
	v_add_f32_e32 v0, v166, v0
	v_add_f32_e32 v0, v167, v0
	v_cmp_ge_f32_e32 vcc, s98, v0
	s_cmp_eq_u64 vcc, exec
	s_cbranch_scc1 .LBB0_537
; DI void attn_item(const Params& p, int item, char* smem) {
;     ...
;     { auto rr = __builtin_amdgcn_permlane32_swap(__float_as_uint(mx), __float_as_uint(mx), false, false);
;       mx = fmaxf(__uint_as_float(rr[0]), __uint_as_float(rr[1])); }
;     if (!__all(mx - mrun <= 8.f)) {
;       const float mn = fmaxf(mrun, mx);
;       const float alpha = __builtin_amdgcn_exp2f(mrun - mn);
;       mrun = mn; lrun *= alpha;
; #pragma unroll
;       for (int i = 0; i < 16; ++i) { o0[i] *= alpha; o1[i] *= alpha; }
;     }
;     float ps = 0.f;
; #pragma unroll
;     for (int i = 0; i < 16; ++i) { p0[i] = __builtin_amdgcn_exp2f(p0[i] - mrun); ps += p0[i]; }
; #pragma unroll
;     for (int i = 0; i < 16; ++i) { p1[i] = __builtin_amdgcn_exp2f(p1[i] - mrun); ps += p1[i]; }
	v_max_f32_e32 v10, v64, v65
	v_max3_f32 v10, v10, v66, v67
	v_max3_f32 v10, v10, v68, v69
	v_max3_f32 v10, v10, v70, v71
	v_max3_f32 v10, v10, v72, v73
	v_max3_f32 v10, v10, v74, v75
	v_max3_f32 v10, v10, v76, v77
	v_max3_f32 v10, v10, v78, v79
	v_max3_f32 v10, v10, v48, v49
	v_max3_f32 v10, v10, v50, v51
	v_max3_f32 v10, v10, v52, v53
	v_max3_f32 v10, v10, v54, v55
	v_max3_f32 v10, v10, v56, v57
	v_max3_f32 v10, v10, v58, v59
	v_max3_f32 v10, v10, v60, v61
	v_max3_f32 v10, v10, v62, v63
	v_mov_b32_e32 v11, v10
	s_nop 1
	v_permlane32_swap_b32_e32 v10, v11
	v_max_f32_e32 v10, v10, v11
	v_max_f32_e32 v11, s99, v10
	v_max_f32_e32 v10, 0, v11
	s_mov_b32 s98, 0x46000000
	v_exp_f32_e64 v10, -v10
	s_mov_b32 s99, 0
	v_sub_f32_e32 v196, v196, v11
	v_mul_f32_e32 v157, v157, v10
	v_pk_mul_f32 v[46:47], v[46:47], v[10:11] op_sel_hi:[1,0]
	v_pk_mul_f32 v[44:45], v[44:45], v[10:11] op_sel_hi:[1,0]
	v_pk_mul_f32 v[42:43], v[42:43], v[10:11] op_sel_hi:[1,0]
	v_pk_mul_f32 v[40:41], v[40:41], v[10:11] op_sel_hi:[1,0]
	v_pk_mul_f32 v[38:39], v[38:39], v[10:11] op_sel_hi:[1,0]
	v_pk_mul_f32 v[36:37], v[36:37], v[10:11] op_sel_hi:[1,0]
	v_pk_mul_f32 v[34:35], v[34:35], v[10:11] op_sel_hi:[1,0]
	v_pk_mul_f32 v[32:33], v[32:33], v[10:11] op_sel_hi:[1,0]
	v_pk_mul_f32 v[30:31], v[30:31], v[10:11] op_sel_hi:[1,0]
	v_pk_mul_f32 v[28:29], v[28:29], v[10:11] op_sel_hi:[1,0]
	v_pk_mul_f32 v[26:27], v[26:27], v[10:11] op_sel_hi:[1,0]
	v_pk_mul_f32 v[24:25], v[24:25], v[10:11] op_sel_hi:[1,0]
	v_pk_mul_f32 v[22:23], v[22:23], v[10:11] op_sel_hi:[1,0]
	v_pk_mul_f32 v[20:21], v[20:21], v[10:11] op_sel_hi:[1,0]
	v_pk_mul_f32 v[18:19], v[18:19], v[10:11] op_sel_hi:[1,0]
	v_pk_mul_f32 v[16:17], v[16:17], v[10:11] op_sel_hi:[1,0]
	v_mov_b32_e32 v197, v196
	v_mov_b32_e32 v198, v196
	v_mov_b32_e32 v199, v196
	v_mov_b32_e32 v200, v196
	v_mov_b32_e32 v201, v196
	v_mov_b32_e32 v202, v196
	v_mov_b32_e32 v203, v196
	v_mov_b32_e32 v204, v196
	v_mov_b32_e32 v205, v196
	v_mov_b32_e32 v206, v196
	v_mov_b32_e32 v207, v196
	v_mov_b32_e32 v208, v196
	v_mov_b32_e32 v209, v196
	v_mov_b32_e32 v210, v196
	v_mov_b32_e32 v211, v196
	v_sub_f32_e32 v64, v64, v11
	v_sub_f32_e32 v65, v65, v11
	v_sub_f32_e32 v66, v66, v11
	v_sub_f32_e32 v67, v67, v11
	v_sub_f32_e32 v68, v68, v11
	v_sub_f32_e32 v69, v69, v11
	v_sub_f32_e32 v70, v70, v11
	v_sub_f32_e32 v71, v71, v11
	v_sub_f32_e32 v72, v72, v11
	v_sub_f32_e32 v73, v73, v11
	v_sub_f32_e32 v74, v74, v11
	v_sub_f32_e32 v75, v75, v11
	v_sub_f32_e32 v76, v76, v11
	v_sub_f32_e32 v77, v77, v11
	v_sub_f32_e32 v78, v78, v11
	v_sub_f32_e32 v79, v79, v11
	v_sub_f32_e32 v48, v48, v11
	v_sub_f32_e32 v49, v49, v11
	v_sub_f32_e32 v50, v50, v11
	v_sub_f32_e32 v51, v51, v11
	v_sub_f32_e32 v52, v52, v11
	v_sub_f32_e32 v53, v53, v11
	v_sub_f32_e32 v54, v54, v11
	v_sub_f32_e32 v55, v55, v11
	v_sub_f32_e32 v56, v56, v11
	v_sub_f32_e32 v57, v57, v11
	v_sub_f32_e32 v58, v58, v11
	v_sub_f32_e32 v59, v59, v11
	v_sub_f32_e32 v60, v60, v11
	v_sub_f32_e32 v61, v61, v11
	v_sub_f32_e32 v62, v62, v11
	v_sub_f32_e32 v63, v63, v11
	v_exp_f32_e32 v168, v64
	v_exp_f32_e32 v169, v65
	v_exp_f32_e32 v170, v66
	v_exp_f32_e32 v171, v67
	v_exp_f32_e32 v172, v68
	v_exp_f32_e32 v173, v69
	v_exp_f32_e32 v174, v70
	v_exp_f32_e32 v175, v71
	v_exp_f32_e32 v176, v72
	v_exp_f32_e32 v177, v73
	v_exp_f32_e32 v178, v74
	v_exp_f32_e32 v179, v75
	v_exp_f32_e32 v180, v76
	v_exp_f32_e32 v181, v77
	v_exp_f32_e32 v182, v78
	v_exp_f32_e32 v183, v79
	v_exp_f32_e32 v184, v48
	v_exp_f32_e32 v185, v49
	v_exp_f32_e32 v186, v50
	v_exp_f32_e32 v187, v51
	v_exp_f32_e32 v188, v52
	v_exp_f32_e32 v189, v53
	v_exp_f32_e32 v190, v54
	v_exp_f32_e32 v191, v55
	v_exp_f32_e32 v158, v56
	v_exp_f32_e32 v159, v57
	v_exp_f32_e32 v160, v58
	v_exp_f32_e32 v161, v59
	v_exp_f32_e32 v164, v60
	v_exp_f32_e32 v165, v61
	v_exp_f32_e32 v166, v62
	v_exp_f32_e32 v167, v63
	v_add_f32_e32 v0, v168, v169
	v_add_f32_e32 v0, v170, v0
	v_add_f32_e32 v0, v171, v0
	v_add_f32_e32 v0, v172, v0
	v_add_f32_e32 v0, v173, v0
	v_add_f32_e32 v0, v174, v0
	v_add_f32_e32 v0, v175, v0
	v_add_f32_e32 v0, v176, v0
	v_add_f32_e32 v0, v177, v0
	v_add_f32_e32 v0, v178, v0
	v_add_f32_e32 v0, v179, v0
	v_add_f32_e32 v0, v180, v0
	v_add_f32_e32 v0, v181, v0
	v_add_f32_e32 v0, v182, v0
	v_add_f32_e32 v0, v183, v0
	v_add_f32_e32 v0, v184, v0
	v_add_f32_e32 v0, v185, v0
	v_add_f32_e32 v0, v186, v0
	v_add_f32_e32 v0, v187, v0
	v_add_f32_e32 v0, v188, v0
	v_add_f32_e32 v0, v189, v0
	v_add_f32_e32 v0, v190, v0
	v_add_f32_e32 v0, v191, v0
	v_add_f32_e32 v0, v158, v0
	v_add_f32_e32 v0, v159, v0
	v_add_f32_e32 v0, v160, v0
	v_add_f32_e32 v0, v161, v0
	v_add_f32_e32 v0, v164, v0
	v_add_f32_e32 v0, v165, v0
	v_add_f32_e32 v0, v166, v0
	v_add_f32_e32 v0, v167, v0
